# FFN epilogue: first conv-weight loads issued before the two exchange barriers instead of after
# baseline (speedup 1.0000x reference)
; #define LAS __attribute__((address_space(3)))
; __device__ __forceinline__ void epi_ffn(const f32x4 (&acc)[2][2][4][2], const Unit& u, char* Cb, const float* __restrict__ cw, const float* __restrict__ cb, float* __restrict__ edge, long edgeN,
;                                         LAS float* E, int wr, int wc, int fr, int fq) {
;     ...
;     asm volatile("s_waitcnt lgkmcnt(0)" ::: "memory");
;     __builtin_amdgcn_s_barrier();
;     __builtin_amdgcn_s_barrier();
;     __builtin_amdgcn_sched_barrier(0);
;     const int f0 = u.pn * 128 + cl;
;     bf16_t* hbase = (bf16_t*)Cb + (long)(u.pm * BM + wr * 64 + fr) * DFF + f0;
; #pragma unroll
;     for (int n = 0; n < 2; ++n) {
;         const f32x4 w0 = *(const f32x4*)(cw + f0 + 16 * n), w1 = *(const f32x4*)(cw + DFF + f0 + 16 * n), w2 = *(const f32x4*)(cw + 2 * DFF + f0 + 16 * n), bb = *(const f32x4*)(cb + f0 + 16 * n);
; #pragma unroll
;         for (int ai = 0; ai < 2; ++ai) {
;             const f32x4 zero = {0.f, 0.f, 0.f, 0.f};
;             f32x4 bup, bdn;
;             if (wr == 1) bup = *(const LAS f32x4*)&E[((0 * 2 + ai) * 2 + 1) * 128 + cl + 16 * n];
.LBB0_507:
	s_or_b64 exec, exec, s[2:3]
	s_waitcnt lgkmcnt(0)
	s_mul_i32 s2, s87, 0x2100
	s_ashr_i32 s3, s2, 31
	s_lshl_b64 s[2:3], s[2:3], 2
	s_add_u32 s2, s12, s2
	s_mul_i32 s8, s87, 0xb00
	s_addc_u32 s3, s13, s3
	s_ashr_i32 s9, s8, 31
	s_waitcnt lgkmcnt(0)
	s_lshl_b64 s[8:9], s[8:9], 2
	s_add_u32 s8, s14, s8
	s_addc_u32 s9, s15, s9
	v_lshl_or_b32 v12, s61, 7, v236
	v_ashrrev_i32_e32 v13, 31, v12
	v_lshlrev_b64 v[134:135], 2, v[12:13]
	v_lshl_add_u64 v[188:189], s[2:3], 0, v[134:135]
	v_add_co_u32_e32 v138, vcc, 0x2000, v188
	v_lshl_add_u64 v[186:187], s[8:9], 0, v[134:135]
	s_nop 0
	v_addc_co_u32_e32 v139, vcc, 0, v189, vcc
	v_add_co_u32_e32 v142, vcc, 0x5000, v188
	global_load_dwordx4 v[134:137], v[188:189], off
	s_nop 0
	v_addc_co_u32_e32 v143, vcc, 0, v189, vcc
	global_load_dwordx4 v[138:141], v[138:139], off offset:3072
	s_nop 0
	global_load_dwordx4 v[142:145], v[142:143], off offset:2048
	s_nop 0
	global_load_dwordx4 v[146:149], v[186:187], off
	s_barrier
	s_barrier
	v_readlane_b32 s2, v254, 54
	v_readlane_b32 s3, v254, 55
	v_mov_b32_e32 v154, 0
	s_andn2_b64 vcc, exec, s[2:3]
	v_cndmask_b32_e64 v10, 0, 1, s[2:3]
	v_cmp_ne_u32_e64 s[40:41], 1, v10
	v_mov_b32_e32 v155, 0
	v_mov_b32_e32 v156, 0
	v_mov_b32_e32 v157, 0
	s_cbranch_vccnz .LBB0_509
	ds_read_b128 v[154:157], v238 offset:512
